# stack: P0 row loads pipelined, tail_fixup partial+ssc loads issued together, final-norm gains preloaded and row loads pipelined, K-loop cleanups, permlane row-max, census pipelined, MLP-up epilogue ho
# speedup vs baseline: 1.0134x; 1.0022x over previous
.LBB0_634:
	v_lshl_add_u64 v[8:9], s[76:77], 0, v[6:7]
	global_load_dwordx4 v[12:15], v[8:9], off offset:32
	global_load_dwordx4 v[16:19], v[8:9], off offset:48
	global_load_dwordx4 v[20:23], v[8:9], off
	global_load_dwordx4 v[24:27], v[8:9], off offset:16
	global_load_dwordx4 v[218:221], v[8:9], off offset:96
	global_load_dwordx4 v[222:225], v[8:9], off offset:112
	global_load_dwordx4 v[226:229], v[8:9], off offset:64
	global_load_dwordx4 v[230:233], v[8:9], off offset:80
	v_add_u32_e32 v2, s36, v2
	v_cmp_lt_i32_e32 vcc, s94, v2
	v_lshl_add_u64 v[6:7], v[6:7], 0, s[42:43]
	s_or_b64 s[4:5], vcc, s[4:5]
	s_waitcnt vmcnt(6)
	v_pk_add_f32 v[14:15], v[14:15], v[18:19]
	v_pk_add_f32 v[12:13], v[12:13], v[16:17]
	s_waitcnt vmcnt(4)
	v_pk_add_f32 v[22:23], v[22:23], v[26:27]
	v_pk_add_f32 v[20:21], v[20:21], v[24:25]
	v_pk_add_f32 v[28:29], v[22:23], v[14:15]
	v_pk_add_f32 v[30:31], v[20:21], v[12:13]
	s_waitcnt vmcnt(2)
	v_pk_add_f32 v[14:15], v[220:221], v[224:225]
	v_pk_add_f32 v[12:13], v[218:219], v[222:223]
	s_waitcnt vmcnt(0)
	v_pk_add_f32 v[8:9], v[228:229], v[232:233]
	v_pk_add_f32 v[20:21], v[226:227], v[230:231]
	v_pk_add_f32 v[8:9], v[8:9], v[14:15]
	v_pk_add_f32 v[12:13], v[20:21], v[12:13]
	v_pk_add_f32 v[8:9], v[28:29], v[8:9]
	v_pk_add_f32 v[12:13], v[30:31], v[12:13]
	s_nop 0
	v_pk_mov_b32 v[14:15], v[12:13], v[8:9] op_sel:[1,0]
	v_mov_b32_e32 v13, v9
	v_pk_add_f32 v[8:9], v[14:15], v[12:13]
	s_nop 0
	v_add_f32_e32 v1, v8, v9
	v_lshl_add_u64 v[8:9], s[76:77], 0, v[4:5]
	v_lshl_add_u64 v[4:5], v[4:5], 0, s[92:93]
	global_store_dword v[8:9], v1, off
	s_andn2_b64 exec, exec, s[4:5]
	s_cbranch_execnz .LBB0_634
